# non-temporal hint on the residual-add epilogue loads/stores of the four out-projection GEMMs
# baseline (speedup 1.0000x reference)
.LBB0_377:
	v_lshl_add_u32 v142, s18, 8, v144
	v_lshl_or_b32 v140, s40, 8, v146
	v_readlane_b32 s52, v255, 7
	v_readlane_b32 s53, v255, 8
	s_nop 2
	s_mov_b64 s[48:49], s[52:53]
	v_readlane_b32 s54, v255, 9
	v_readlane_b32 s55, v255, 10
	v_readlane_b32 s56, v255, 11
	v_readlane_b32 s57, v255, 12
	v_readlane_b32 s58, v255, 13
	v_readlane_b32 s59, v255, 14
	v_readlane_b32 s60, v255, 15
	v_readlane_b32 s61, v255, 16
	v_readlane_b32 s62, v255, 17
	v_readlane_b32 s63, v255, 18
	v_readlane_b32 s64, v255, 19
	v_readlane_b32 s65, v255, 20
	v_readlane_b32 s66, v255, 21
	v_readlane_b32 s67, v255, 22
	s_mov_b64 s[52:53], s[56:57]
	s_andn2_b64 vcc, exec, s[2:3]
	s_mov_b64 s[2:3], -1
	s_mov_b64 s[54:55], s[58:59]
	s_mov_b64 s[56:57], s[60:61]
	s_mov_b64 s[58:59], s[62:63]
	s_mov_b64 s[60:61], s[64:65]
	s_mov_b64 s[62:63], s[66:67]
	v_ashrrev_i32_e32 v141, 31, v140
	v_mov_b32_e32 v246, v142
	v_ashrrev_i32_e32 v247, 31, v246
	v_lshlrev_b64 v[246:247], 11, v[246:247]
	v_lshl_add_u64 v[246:247], v[246:247], 0, v[140:141]
	v_lshlrev_b64 v[246:247], 2, v[246:247]
	v_lshl_add_u64 v[248:249], s[48:49], 0, v[246:247]
	global_load_dwordx4 v[160:163], v[248:249], off nt
	global_load_dwordx4 v[164:167], v[248:249], off offset:64 nt
	global_load_dwordx4 v[168:171], v[248:249], off offset:512 nt
	global_load_dwordx4 v[172:175], v[248:249], off offset:576 nt
	v_or_b32_e32 v246, 0x10, v142
	v_ashrrev_i32_e32 v247, 31, v246
	v_lshlrev_b64 v[246:247], 11, v[246:247]
	v_lshl_add_u64 v[246:247], v[246:247], 0, v[140:141]
	v_lshlrev_b64 v[246:247], 2, v[246:247]
	v_lshl_add_u64 v[248:249], s[48:49], 0, v[246:247]
	global_load_dwordx4 v[176:179], v[248:249], off nt
	global_load_dwordx4 v[180:183], v[248:249], off offset:64 nt
	global_load_dwordx4 v[184:187], v[248:249], off offset:512 nt
	global_load_dwordx4 v[188:191], v[248:249], off offset:576 nt
	v_or_b32_e32 v246, 0x20, v142
	v_ashrrev_i32_e32 v247, 31, v246
	v_lshlrev_b64 v[246:247], 11, v[246:247]
	v_lshl_add_u64 v[246:247], v[246:247], 0, v[140:141]
	v_lshlrev_b64 v[246:247], 2, v[246:247]
	v_lshl_add_u64 v[248:249], s[48:49], 0, v[246:247]
	global_load_dwordx4 v[192:195], v[248:249], off nt
	global_load_dwordx4 v[196:199], v[248:249], off offset:64 nt
	global_load_dwordx4 v[200:203], v[248:249], off offset:512 nt
	global_load_dwordx4 v[204:207], v[248:249], off offset:576 nt
	v_or_b32_e32 v246, 0x30, v142
	v_ashrrev_i32_e32 v247, 31, v246
	v_lshlrev_b64 v[246:247], 11, v[246:247]
	v_lshl_add_u64 v[246:247], v[246:247], 0, v[140:141]
	v_lshlrev_b64 v[246:247], 2, v[246:247]
	v_lshl_add_u64 v[248:249], s[48:49], 0, v[246:247]
	global_load_dwordx4 v[214:217], v[248:249], off nt
	global_load_dwordx4 v[218:221], v[248:249], off offset:64 nt
	global_load_dwordx4 v[222:225], v[248:249], off offset:512 nt
	global_load_dwordx4 v[226:229], v[248:249], off offset:576 nt
	v_or_b32_e32 v246, 0x80, v142
	v_ashrrev_i32_e32 v247, 31, v246
	v_lshlrev_b64 v[246:247], 11, v[246:247]
	v_lshl_add_u64 v[246:247], v[246:247], 0, v[140:141]
	v_lshlrev_b64 v[246:247], 2, v[246:247]
	v_lshl_add_u64 v[248:249], s[48:49], 0, v[246:247]
	global_load_dwordx4 v[230:233], v[248:249], off nt
	global_load_dwordx4 v[234:237], v[248:249], off offset:64 nt
	global_load_dwordx4 v[238:241], v[248:249], off offset:512 nt
	global_load_dwordx4 v[242:245], v[248:249], off offset:576 nt
	s_waitcnt vmcnt(16)
	v_pk_add_f32 v[160:161], v[124:125], v[160:161]
	v_pk_add_f32 v[162:163], v[126:127], v[162:163]
	v_pk_add_f32 v[164:165], v[120:121], v[164:165]
	v_pk_add_f32 v[166:167], v[122:123], v[166:167]
	v_pk_add_f32 v[168:169], v[116:117], v[168:169]
	v_pk_add_f32 v[170:171], v[118:119], v[170:171]
	v_pk_add_f32 v[172:173], v[104:105], v[172:173]
	v_pk_add_f32 v[174:175], v[106:107], v[174:175]
	v_mov_b32_e32 v246, v142
	v_ashrrev_i32_e32 v247, 31, v246
	v_lshlrev_b64 v[246:247], 11, v[246:247]
	v_lshl_add_u64 v[246:247], v[246:247], 0, v[140:141]
	v_lshlrev_b64 v[246:247], 2, v[246:247]
	v_lshl_add_u64 v[250:251], s[78:79], 0, v[246:247]
	global_store_dwordx4 v[250:251], v[160:163], off nt
	global_store_dwordx4 v[250:251], v[164:167], off offset:64 nt
	global_store_dwordx4 v[250:251], v[168:171], off offset:512 nt
	global_store_dwordx4 v[250:251], v[172:175], off offset:576 nt
	v_or_b32_e32 v246, 0x90, v142
	v_ashrrev_i32_e32 v247, 31, v246
	v_lshlrev_b64 v[246:247], 11, v[246:247]
	v_lshl_add_u64 v[246:247], v[246:247], 0, v[140:141]
	v_lshlrev_b64 v[246:247], 2, v[246:247]
	v_lshl_add_u64 v[248:249], s[48:49], 0, v[246:247]
	global_load_dwordx4 v[160:163], v[248:249], off nt
	global_load_dwordx4 v[164:167], v[248:249], off offset:64 nt
	global_load_dwordx4 v[168:171], v[248:249], off offset:512 nt
	global_load_dwordx4 v[172:175], v[248:249], off offset:576 nt
	s_waitcnt vmcnt(20)
	v_pk_add_f32 v[176:177], v[112:113], v[176:177]
	v_pk_add_f32 v[178:179], v[114:115], v[178:179]
	v_pk_add_f32 v[180:181], v[108:109], v[180:181]
	v_pk_add_f32 v[182:183], v[110:111], v[182:183]
	v_pk_add_f32 v[184:185], v[100:101], v[184:185]
	v_pk_add_f32 v[186:187], v[102:103], v[186:187]
	v_pk_add_f32 v[188:189], v[88:89], v[188:189]
	v_pk_add_f32 v[190:191], v[90:91], v[190:191]
	v_or_b32_e32 v246, 0x10, v142
	v_ashrrev_i32_e32 v247, 31, v246
	v_lshlrev_b64 v[246:247], 11, v[246:247]
	v_lshl_add_u64 v[246:247], v[246:247], 0, v[140:141]
	v_lshlrev_b64 v[246:247], 2, v[246:247]
	v_lshl_add_u64 v[250:251], s[78:79], 0, v[246:247]
	global_store_dwordx4 v[250:251], v[176:179], off nt
	global_store_dwordx4 v[250:251], v[180:183], off offset:64 nt
	global_store_dwordx4 v[250:251], v[184:187], off offset:512 nt
	global_store_dwordx4 v[250:251], v[188:191], off offset:576 nt
	v_or_b32_e32 v246, 0xa0, v142
	v_ashrrev_i32_e32 v247, 31, v246
	v_lshlrev_b64 v[246:247], 11, v[246:247]
	v_lshl_add_u64 v[246:247], v[246:247], 0, v[140:141]
	v_lshlrev_b64 v[246:247], 2, v[246:247]
	v_lshl_add_u64 v[248:249], s[48:49], 0, v[246:247]
	global_load_dwordx4 v[176:179], v[248:249], off nt
	global_load_dwordx4 v[180:183], v[248:249], off offset:64 nt
	global_load_dwordx4 v[184:187], v[248:249], off offset:512 nt
	global_load_dwordx4 v[188:191], v[248:249], off offset:576 nt
	s_waitcnt vmcnt(24)
	v_pk_add_f32 v[192:193], v[96:97], v[192:193]
	v_pk_add_f32 v[194:195], v[98:99], v[194:195]
	v_pk_add_f32 v[196:197], v[92:93], v[196:197]
	v_pk_add_f32 v[198:199], v[94:95], v[198:199]
	v_pk_add_f32 v[200:201], v[84:85], v[200:201]
	v_pk_add_f32 v[202:203], v[86:87], v[202:203]
	v_pk_add_f32 v[204:205], v[72:73], v[204:205]
	v_pk_add_f32 v[206:207], v[74:75], v[206:207]
	v_or_b32_e32 v246, 0x20, v142
	v_ashrrev_i32_e32 v247, 31, v246
	v_lshlrev_b64 v[246:247], 11, v[246:247]
	v_lshl_add_u64 v[246:247], v[246:247], 0, v[140:141]
	v_lshlrev_b64 v[246:247], 2, v[246:247]
	v_lshl_add_u64 v[250:251], s[78:79], 0, v[246:247]
	global_store_dwordx4 v[250:251], v[192:195], off nt
	global_store_dwordx4 v[250:251], v[196:199], off offset:64 nt
	global_store_dwordx4 v[250:251], v[200:203], off offset:512 nt
	global_store_dwordx4 v[250:251], v[204:207], off offset:576 nt
	v_or_b32_e32 v246, 0xb0, v142
	v_ashrrev_i32_e32 v247, 31, v246
	v_lshlrev_b64 v[246:247], 11, v[246:247]
	v_lshl_add_u64 v[246:247], v[246:247], 0, v[140:141]
	v_lshlrev_b64 v[246:247], 2, v[246:247]
	v_lshl_add_u64 v[248:249], s[48:49], 0, v[246:247]
	global_load_dwordx4 v[192:195], v[248:249], off nt
	global_load_dwordx4 v[196:199], v[248:249], off offset:64 nt
	global_load_dwordx4 v[200:203], v[248:249], off offset:512 nt
	global_load_dwordx4 v[204:207], v[248:249], off offset:576 nt
	s_waitcnt vmcnt(28)
	v_pk_add_f32 v[214:215], v[80:81], v[214:215]
	v_pk_add_f32 v[216:217], v[82:83], v[216:217]
	v_pk_add_f32 v[218:219], v[76:77], v[218:219]
	v_pk_add_f32 v[220:221], v[78:79], v[220:221]
	v_pk_add_f32 v[222:223], v[68:69], v[222:223]
	v_pk_add_f32 v[224:225], v[70:71], v[224:225]
	v_pk_add_f32 v[226:227], v[64:65], v[226:227]
	v_pk_add_f32 v[228:229], v[66:67], v[228:229]
	v_or_b32_e32 v246, 0x30, v142
	v_ashrrev_i32_e32 v247, 31, v246
	v_lshlrev_b64 v[246:247], 11, v[246:247]
	v_lshl_add_u64 v[246:247], v[246:247], 0, v[140:141]
	v_lshlrev_b64 v[246:247], 2, v[246:247]
	v_lshl_add_u64 v[250:251], s[78:79], 0, v[246:247]
	global_store_dwordx4 v[250:251], v[214:217], off nt
	global_store_dwordx4 v[250:251], v[218:221], off offset:64 nt
	global_store_dwordx4 v[250:251], v[222:225], off offset:512 nt
	global_store_dwordx4 v[250:251], v[226:229], off offset:576 nt
	s_waitcnt vmcnt(28)
	v_pk_add_f32 v[230:231], v[60:61], v[230:231]
	v_pk_add_f32 v[232:233], v[62:63], v[232:233]
	v_pk_add_f32 v[234:235], v[56:57], v[234:235]
	v_pk_add_f32 v[236:237], v[58:59], v[236:237]
	v_pk_add_f32 v[238:239], v[52:53], v[238:239]
	v_pk_add_f32 v[240:241], v[54:55], v[240:241]
	v_pk_add_f32 v[242:243], v[40:41], v[242:243]
	v_pk_add_f32 v[244:245], v[42:43], v[244:245]
	v_or_b32_e32 v246, 0x80, v142
	v_ashrrev_i32_e32 v247, 31, v246
	v_lshlrev_b64 v[246:247], 11, v[246:247]
	v_lshl_add_u64 v[246:247], v[246:247], 0, v[140:141]
	v_lshlrev_b64 v[246:247], 2, v[246:247]
	v_lshl_add_u64 v[250:251], s[78:79], 0, v[246:247]
	global_store_dwordx4 v[250:251], v[230:233], off nt
	global_store_dwordx4 v[250:251], v[234:237], off offset:64 nt
	global_store_dwordx4 v[250:251], v[238:241], off offset:512 nt
	global_store_dwordx4 v[250:251], v[242:245], off offset:576 nt
	s_waitcnt vmcnt(24)
	v_pk_add_f32 v[160:161], v[48:49], v[160:161]
	v_pk_add_f32 v[162:163], v[50:51], v[162:163]
	v_pk_add_f32 v[164:165], v[44:45], v[164:165]
	v_pk_add_f32 v[166:167], v[46:47], v[166:167]
	v_pk_add_f32 v[168:169], v[36:37], v[168:169]
	v_pk_add_f32 v[170:171], v[38:39], v[170:171]
	v_pk_add_f32 v[172:173], v[24:25], v[172:173]
	v_pk_add_f32 v[174:175], v[26:27], v[174:175]
	v_or_b32_e32 v246, 0x90, v142
	v_ashrrev_i32_e32 v247, 31, v246
	v_lshlrev_b64 v[246:247], 11, v[246:247]
	v_lshl_add_u64 v[246:247], v[246:247], 0, v[140:141]
	v_lshlrev_b64 v[246:247], 2, v[246:247]
	v_lshl_add_u64 v[250:251], s[78:79], 0, v[246:247]
	global_store_dwordx4 v[250:251], v[160:163], off nt
	global_store_dwordx4 v[250:251], v[164:167], off offset:64 nt
	global_store_dwordx4 v[250:251], v[168:171], off offset:512 nt
	global_store_dwordx4 v[250:251], v[172:175], off offset:576 nt
	s_waitcnt vmcnt(20)
	v_pk_add_f32 v[176:177], v[32:33], v[176:177]
	v_pk_add_f32 v[178:179], v[34:35], v[178:179]
	v_pk_add_f32 v[180:181], v[28:29], v[180:181]
	v_pk_add_f32 v[182:183], v[30:31], v[182:183]
	v_pk_add_f32 v[184:185], v[20:21], v[184:185]
	v_pk_add_f32 v[186:187], v[22:23], v[186:187]
	v_pk_add_f32 v[188:189], v[8:9], v[188:189]
	v_pk_add_f32 v[190:191], v[10:11], v[190:191]
	v_or_b32_e32 v246, 0xa0, v142
	v_ashrrev_i32_e32 v247, 31, v246
	v_lshlrev_b64 v[246:247], 11, v[246:247]
	v_lshl_add_u64 v[246:247], v[246:247], 0, v[140:141]
	v_lshlrev_b64 v[246:247], 2, v[246:247]
	v_lshl_add_u64 v[250:251], s[78:79], 0, v[246:247]
	global_store_dwordx4 v[250:251], v[176:179], off nt
	global_store_dwordx4 v[250:251], v[180:183], off offset:64 nt
	global_store_dwordx4 v[250:251], v[184:187], off offset:512 nt
	global_store_dwordx4 v[250:251], v[188:191], off offset:576 nt
	s_waitcnt vmcnt(16)
	v_pk_add_f32 v[192:193], v[16:17], v[192:193]
	v_pk_add_f32 v[194:195], v[18:19], v[194:195]
	v_pk_add_f32 v[196:197], v[12:13], v[196:197]
	v_pk_add_f32 v[198:199], v[14:15], v[198:199]
	v_pk_add_f32 v[200:201], v[4:5], v[200:201]
	v_pk_add_f32 v[202:203], v[6:7], v[202:203]
	v_pk_add_f32 v[204:205], v[0:1], v[204:205]
	v_pk_add_f32 v[206:207], v[2:3], v[206:207]
	v_or_b32_e32 v246, 0xb0, v142
	v_ashrrev_i32_e32 v247, 31, v246
	v_lshlrev_b64 v[246:247], 11, v[246:247]
	v_lshl_add_u64 v[246:247], v[246:247], 0, v[140:141]
	v_lshlrev_b64 v[246:247], 2, v[246:247]
	v_lshl_add_u64 v[250:251], s[78:79], 0, v[246:247]
	global_store_dwordx4 v[250:251], v[192:195], off nt
	global_store_dwordx4 v[250:251], v[196:199], off offset:64 nt
	global_store_dwordx4 v[250:251], v[200:203], off offset:512 nt
	global_store_dwordx4 v[250:251], v[204:207], off offset:576 nt
	s_cbranch_vccnz .LBB0_366
	s_andn2_b64 vcc, exec, s[0:1]
	s_cbranch_vccnz .LBB0_365
	s_barrier
	s_branch .LBB0_365

.LBB0_739:
	v_lshl_add_u32 v142, s18, 8, v144
	v_lshl_or_b32 v140, s40, 8, v146
	s_andn2_b64 vcc, exec, s[2:3]
	s_mov_b64 s[2:3], -1
	v_ashrrev_i32_e32 v141, 31, v140
	v_mov_b32_e32 v246, v142
	v_ashrrev_i32_e32 v247, 31, v246
	v_lshlrev_b64 v[246:247], 11, v[246:247]
	v_lshl_add_u64 v[246:247], v[246:247], 0, v[140:141]
	v_lshlrev_b64 v[246:247], 2, v[246:247]
	v_lshl_add_u64 v[248:249], s[78:79], 0, v[246:247]
	global_load_dwordx4 v[160:163], v[248:249], off nt
	global_load_dwordx4 v[164:167], v[248:249], off offset:64 nt
	global_load_dwordx4 v[168:171], v[248:249], off offset:512 nt
	global_load_dwordx4 v[172:175], v[248:249], off offset:576 nt
	v_or_b32_e32 v246, 0x10, v142
	v_ashrrev_i32_e32 v247, 31, v246
	v_lshlrev_b64 v[246:247], 11, v[246:247]
	v_lshl_add_u64 v[246:247], v[246:247], 0, v[140:141]
	v_lshlrev_b64 v[246:247], 2, v[246:247]
	v_lshl_add_u64 v[248:249], s[78:79], 0, v[246:247]
	global_load_dwordx4 v[176:179], v[248:249], off nt
	global_load_dwordx4 v[180:183], v[248:249], off offset:64 nt
	global_load_dwordx4 v[184:187], v[248:249], off offset:512 nt
	global_load_dwordx4 v[188:191], v[248:249], off offset:576 nt
	v_or_b32_e32 v246, 0x20, v142
	v_ashrrev_i32_e32 v247, 31, v246
	v_lshlrev_b64 v[246:247], 11, v[246:247]
	v_lshl_add_u64 v[246:247], v[246:247], 0, v[140:141]
	v_lshlrev_b64 v[246:247], 2, v[246:247]
	v_lshl_add_u64 v[248:249], s[78:79], 0, v[246:247]
	global_load_dwordx4 v[192:195], v[248:249], off nt
	global_load_dwordx4 v[196:199], v[248:249], off offset:64 nt
	global_load_dwordx4 v[200:203], v[248:249], off offset:512 nt
	global_load_dwordx4 v[204:207], v[248:249], off offset:576 nt
	v_or_b32_e32 v246, 0x30, v142
	v_ashrrev_i32_e32 v247, 31, v246
	v_lshlrev_b64 v[246:247], 11, v[246:247]
	v_lshl_add_u64 v[246:247], v[246:247], 0, v[140:141]
	v_lshlrev_b64 v[246:247], 2, v[246:247]
	v_lshl_add_u64 v[248:249], s[78:79], 0, v[246:247]
	global_load_dwordx4 v[214:217], v[248:249], off nt
	global_load_dwordx4 v[218:221], v[248:249], off offset:64 nt
	global_load_dwordx4 v[222:225], v[248:249], off offset:512 nt
	global_load_dwordx4 v[226:229], v[248:249], off offset:576 nt
	v_or_b32_e32 v246, 0x80, v142
	v_ashrrev_i32_e32 v247, 31, v246
	v_lshlrev_b64 v[246:247], 11, v[246:247]
	v_lshl_add_u64 v[246:247], v[246:247], 0, v[140:141]
	v_lshlrev_b64 v[246:247], 2, v[246:247]
	v_lshl_add_u64 v[248:249], s[78:79], 0, v[246:247]
	global_load_dwordx4 v[230:233], v[248:249], off nt
	global_load_dwordx4 v[234:237], v[248:249], off offset:64 nt
	global_load_dwordx4 v[238:241], v[248:249], off offset:512 nt
	global_load_dwordx4 v[242:245], v[248:249], off offset:576 nt
	s_waitcnt vmcnt(16)
	v_pk_add_f32 v[160:161], v[124:125], v[160:161]
	v_pk_add_f32 v[162:163], v[126:127], v[162:163]
	v_pk_add_f32 v[164:165], v[120:121], v[164:165]
	v_pk_add_f32 v[166:167], v[122:123], v[166:167]
	v_pk_add_f32 v[168:169], v[108:109], v[168:169]
	v_pk_add_f32 v[170:171], v[110:111], v[170:171]
	v_pk_add_f32 v[172:173], v[104:105], v[172:173]
	v_pk_add_f32 v[174:175], v[106:107], v[174:175]
	v_mov_b32_e32 v246, v142
	v_ashrrev_i32_e32 v247, 31, v246
	v_lshlrev_b64 v[246:247], 11, v[246:247]
	v_lshl_add_u64 v[246:247], v[246:247], 0, v[140:141]
	v_lshlrev_b64 v[246:247], 2, v[246:247]
	v_lshl_add_u64 v[250:251], s[78:79], 0, v[246:247]
	global_store_dwordx4 v[250:251], v[160:163], off nt
	global_store_dwordx4 v[250:251], v[164:167], off offset:64 nt
	global_store_dwordx4 v[250:251], v[168:171], off offset:512 nt
	global_store_dwordx4 v[250:251], v[172:175], off offset:576 nt
	v_or_b32_e32 v246, 0x90, v142
	v_ashrrev_i32_e32 v247, 31, v246
	v_lshlrev_b64 v[246:247], 11, v[246:247]
	v_lshl_add_u64 v[246:247], v[246:247], 0, v[140:141]
	v_lshlrev_b64 v[246:247], 2, v[246:247]
	v_lshl_add_u64 v[248:249], s[78:79], 0, v[246:247]
	global_load_dwordx4 v[160:163], v[248:249], off nt
	global_load_dwordx4 v[164:167], v[248:249], off offset:64 nt
	global_load_dwordx4 v[168:171], v[248:249], off offset:512 nt
	global_load_dwordx4 v[172:175], v[248:249], off offset:576 nt
	s_waitcnt vmcnt(20)
	v_pk_add_f32 v[176:177], v[116:117], v[176:177]
	v_pk_add_f32 v[178:179], v[118:119], v[178:179]
	v_pk_add_f32 v[180:181], v[112:113], v[180:181]
	v_pk_add_f32 v[182:183], v[114:115], v[182:183]
	v_pk_add_f32 v[184:185], v[100:101], v[184:185]
	v_pk_add_f32 v[186:187], v[102:103], v[186:187]
	v_pk_add_f32 v[188:189], v[96:97], v[188:189]
	v_pk_add_f32 v[190:191], v[98:99], v[190:191]
	v_or_b32_e32 v246, 0x10, v142
	v_ashrrev_i32_e32 v247, 31, v246
	v_lshlrev_b64 v[246:247], 11, v[246:247]
	v_lshl_add_u64 v[246:247], v[246:247], 0, v[140:141]
	v_lshlrev_b64 v[246:247], 2, v[246:247]
	v_lshl_add_u64 v[250:251], s[78:79], 0, v[246:247]
	global_store_dwordx4 v[250:251], v[176:179], off nt
	global_store_dwordx4 v[250:251], v[180:183], off offset:64 nt
	global_store_dwordx4 v[250:251], v[184:187], off offset:512 nt
	global_store_dwordx4 v[250:251], v[188:191], off offset:576 nt
	v_or_b32_e32 v246, 0xa0, v142
	v_ashrrev_i32_e32 v247, 31, v246
	v_lshlrev_b64 v[246:247], 11, v[246:247]
	v_lshl_add_u64 v[246:247], v[246:247], 0, v[140:141]
	v_lshlrev_b64 v[246:247], 2, v[246:247]
	v_lshl_add_u64 v[248:249], s[78:79], 0, v[246:247]
	global_load_dwordx4 v[176:179], v[248:249], off nt
	global_load_dwordx4 v[180:183], v[248:249], off offset:64 nt
	global_load_dwordx4 v[184:187], v[248:249], off offset:512 nt
	global_load_dwordx4 v[188:191], v[248:249], off offset:576 nt
	s_waitcnt vmcnt(24)
	v_pk_add_f32 v[192:193], v[92:93], v[192:193]
	v_pk_add_f32 v[194:195], v[94:95], v[194:195]
	v_pk_add_f32 v[196:197], v[88:89], v[196:197]
	v_pk_add_f32 v[198:199], v[90:91], v[198:199]
	v_pk_add_f32 v[200:201], v[76:77], v[200:201]
	v_pk_add_f32 v[202:203], v[78:79], v[202:203]
	v_pk_add_f32 v[204:205], v[72:73], v[204:205]
	v_pk_add_f32 v[206:207], v[74:75], v[206:207]
	v_or_b32_e32 v246, 0x20, v142
	v_ashrrev_i32_e32 v247, 31, v246
	v_lshlrev_b64 v[246:247], 11, v[246:247]
	v_lshl_add_u64 v[246:247], v[246:247], 0, v[140:141]
	v_lshlrev_b64 v[246:247], 2, v[246:247]
	v_lshl_add_u64 v[250:251], s[78:79], 0, v[246:247]
	global_store_dwordx4 v[250:251], v[192:195], off nt
	global_store_dwordx4 v[250:251], v[196:199], off offset:64 nt
	global_store_dwordx4 v[250:251], v[200:203], off offset:512 nt
	global_store_dwordx4 v[250:251], v[204:207], off offset:576 nt
	v_or_b32_e32 v246, 0xb0, v142
	v_ashrrev_i32_e32 v247, 31, v246
	v_lshlrev_b64 v[246:247], 11, v[246:247]
	v_lshl_add_u64 v[246:247], v[246:247], 0, v[140:141]
	v_lshlrev_b64 v[246:247], 2, v[246:247]
	v_lshl_add_u64 v[248:249], s[78:79], 0, v[246:247]
	global_load_dwordx4 v[192:195], v[248:249], off nt
	global_load_dwordx4 v[196:199], v[248:249], off offset:64 nt
	global_load_dwordx4 v[200:203], v[248:249], off offset:512 nt
	global_load_dwordx4 v[204:207], v[248:249], off offset:576 nt
	s_waitcnt vmcnt(28)
	v_pk_add_f32 v[214:215], v[84:85], v[214:215]
	v_pk_add_f32 v[216:217], v[86:87], v[216:217]
	v_pk_add_f32 v[218:219], v[80:81], v[218:219]
	v_pk_add_f32 v[220:221], v[82:83], v[220:221]
	v_pk_add_f32 v[222:223], v[68:69], v[222:223]
	v_pk_add_f32 v[224:225], v[70:71], v[224:225]
	v_pk_add_f32 v[226:227], v[64:65], v[226:227]
	v_pk_add_f32 v[228:229], v[66:67], v[228:229]
	v_or_b32_e32 v246, 0x30, v142
	v_ashrrev_i32_e32 v247, 31, v246
	v_lshlrev_b64 v[246:247], 11, v[246:247]
	v_lshl_add_u64 v[246:247], v[246:247], 0, v[140:141]
	v_lshlrev_b64 v[246:247], 2, v[246:247]
	v_lshl_add_u64 v[250:251], s[78:79], 0, v[246:247]
	global_store_dwordx4 v[250:251], v[214:217], off nt
	global_store_dwordx4 v[250:251], v[218:221], off offset:64 nt
	global_store_dwordx4 v[250:251], v[222:225], off offset:512 nt
	global_store_dwordx4 v[250:251], v[226:229], off offset:576 nt
	s_waitcnt vmcnt(28)
	v_pk_add_f32 v[230:231], v[60:61], v[230:231]
	v_pk_add_f32 v[232:233], v[62:63], v[232:233]
	v_pk_add_f32 v[234:235], v[56:57], v[234:235]
	v_pk_add_f32 v[236:237], v[58:59], v[236:237]
	v_pk_add_f32 v[238:239], v[44:45], v[238:239]
	v_pk_add_f32 v[240:241], v[46:47], v[240:241]
	v_pk_add_f32 v[242:243], v[40:41], v[242:243]
	v_pk_add_f32 v[244:245], v[42:43], v[244:245]
	v_or_b32_e32 v246, 0x80, v142
	v_ashrrev_i32_e32 v247, 31, v246
	v_lshlrev_b64 v[246:247], 11, v[246:247]
	v_lshl_add_u64 v[246:247], v[246:247], 0, v[140:141]
	v_lshlrev_b64 v[246:247], 2, v[246:247]
	v_lshl_add_u64 v[250:251], s[78:79], 0, v[246:247]
	global_store_dwordx4 v[250:251], v[230:233], off nt
	global_store_dwordx4 v[250:251], v[234:237], off offset:64 nt
	global_store_dwordx4 v[250:251], v[238:241], off offset:512 nt
	global_store_dwordx4 v[250:251], v[242:245], off offset:576 nt
	s_waitcnt vmcnt(24)
	v_pk_add_f32 v[160:161], v[52:53], v[160:161]
	v_pk_add_f32 v[162:163], v[54:55], v[162:163]
	v_pk_add_f32 v[164:165], v[48:49], v[164:165]
	v_pk_add_f32 v[166:167], v[50:51], v[166:167]
	v_pk_add_f32 v[168:169], v[36:37], v[168:169]
	v_pk_add_f32 v[170:171], v[38:39], v[170:171]
	v_pk_add_f32 v[172:173], v[32:33], v[172:173]
	v_pk_add_f32 v[174:175], v[34:35], v[174:175]
	v_or_b32_e32 v246, 0x90, v142
	v_ashrrev_i32_e32 v247, 31, v246
	v_lshlrev_b64 v[246:247], 11, v[246:247]
	v_lshl_add_u64 v[246:247], v[246:247], 0, v[140:141]
	v_lshlrev_b64 v[246:247], 2, v[246:247]
	v_lshl_add_u64 v[250:251], s[78:79], 0, v[246:247]
	global_store_dwordx4 v[250:251], v[160:163], off nt
	global_store_dwordx4 v[250:251], v[164:167], off offset:64 nt
	global_store_dwordx4 v[250:251], v[168:171], off offset:512 nt
	global_store_dwordx4 v[250:251], v[172:175], off offset:576 nt
	s_waitcnt vmcnt(20)
	v_pk_add_f32 v[176:177], v[28:29], v[176:177]
	v_pk_add_f32 v[178:179], v[30:31], v[178:179]
	v_pk_add_f32 v[180:181], v[24:25], v[180:181]
	v_pk_add_f32 v[182:183], v[26:27], v[182:183]
	v_pk_add_f32 v[184:185], v[12:13], v[184:185]
	v_pk_add_f32 v[186:187], v[14:15], v[186:187]
	v_pk_add_f32 v[188:189], v[8:9], v[188:189]
	v_pk_add_f32 v[190:191], v[10:11], v[190:191]
	v_or_b32_e32 v246, 0xa0, v142
	v_ashrrev_i32_e32 v247, 31, v246
	v_lshlrev_b64 v[246:247], 11, v[246:247]
	v_lshl_add_u64 v[246:247], v[246:247], 0, v[140:141]
	v_lshlrev_b64 v[246:247], 2, v[246:247]
	v_lshl_add_u64 v[250:251], s[78:79], 0, v[246:247]
	global_store_dwordx4 v[250:251], v[176:179], off nt
	global_store_dwordx4 v[250:251], v[180:183], off offset:64 nt
	global_store_dwordx4 v[250:251], v[184:187], off offset:512 nt
	global_store_dwordx4 v[250:251], v[188:191], off offset:576 nt
	s_waitcnt vmcnt(16)
	v_pk_add_f32 v[192:193], v[20:21], v[192:193]
	v_pk_add_f32 v[194:195], v[22:23], v[194:195]
	v_pk_add_f32 v[196:197], v[16:17], v[196:197]
	v_pk_add_f32 v[198:199], v[18:19], v[198:199]
	v_pk_add_f32 v[200:201], v[4:5], v[200:201]
	v_pk_add_f32 v[202:203], v[6:7], v[202:203]
	v_pk_add_f32 v[204:205], v[0:1], v[204:205]
	v_pk_add_f32 v[206:207], v[2:3], v[206:207]
	v_or_b32_e32 v246, 0xb0, v142
	v_ashrrev_i32_e32 v247, 31, v246
	v_lshlrev_b64 v[246:247], 11, v[246:247]
	v_lshl_add_u64 v[246:247], v[246:247], 0, v[140:141]
	v_lshlrev_b64 v[246:247], 2, v[246:247]
	v_lshl_add_u64 v[250:251], s[78:79], 0, v[246:247]
	global_store_dwordx4 v[250:251], v[192:195], off nt
	global_store_dwordx4 v[250:251], v[196:199], off offset:64 nt
	global_store_dwordx4 v[250:251], v[200:203], off offset:512 nt
	global_store_dwordx4 v[250:251], v[204:207], off offset:576 nt
	s_cbranch_vccnz .LBB0_728
	s_andn2_b64 vcc, exec, s[0:1]
	s_cbranch_vccnz .LBB0_727
	s_barrier
	s_branch .LBB0_727

.LBB0_1347:
	v_lshl_add_u32 v142, s16, 8, v144
	v_lshl_or_b32 v140, s39, 8, v146
	s_andn2_b64 vcc, exec, s[2:3]
	s_mov_b64 s[2:3], -1
	v_ashrrev_i32_e32 v141, 31, v140
	v_mov_b32_e32 v246, v142
	v_ashrrev_i32_e32 v247, 31, v246
	v_lshlrev_b64 v[246:247], 11, v[246:247]
	v_lshl_add_u64 v[246:247], v[246:247], 0, v[140:141]
	v_lshlrev_b64 v[246:247], 2, v[246:247]
	v_lshl_add_u64 v[248:249], s[78:79], 0, v[246:247]
	global_load_dwordx4 v[160:163], v[248:249], off nt
	global_load_dwordx4 v[164:167], v[248:249], off offset:64 nt
	global_load_dwordx4 v[168:171], v[248:249], off offset:512 nt
	global_load_dwordx4 v[172:175], v[248:249], off offset:576 nt
	v_or_b32_e32 v246, 0x10, v142
	v_ashrrev_i32_e32 v247, 31, v246
	v_lshlrev_b64 v[246:247], 11, v[246:247]
	v_lshl_add_u64 v[246:247], v[246:247], 0, v[140:141]
	v_lshlrev_b64 v[246:247], 2, v[246:247]
	v_lshl_add_u64 v[248:249], s[78:79], 0, v[246:247]
	global_load_dwordx4 v[176:179], v[248:249], off nt
	global_load_dwordx4 v[180:183], v[248:249], off offset:64 nt
	global_load_dwordx4 v[184:187], v[248:249], off offset:512 nt
	global_load_dwordx4 v[188:191], v[248:249], off offset:576 nt
	v_or_b32_e32 v246, 0x20, v142
	v_ashrrev_i32_e32 v247, 31, v246
	v_lshlrev_b64 v[246:247], 11, v[246:247]
	v_lshl_add_u64 v[246:247], v[246:247], 0, v[140:141]
	v_lshlrev_b64 v[246:247], 2, v[246:247]
	v_lshl_add_u64 v[248:249], s[78:79], 0, v[246:247]
	global_load_dwordx4 v[192:195], v[248:249], off nt
	global_load_dwordx4 v[196:199], v[248:249], off offset:64 nt
	global_load_dwordx4 v[200:203], v[248:249], off offset:512 nt
	global_load_dwordx4 v[204:207], v[248:249], off offset:576 nt
	v_or_b32_e32 v246, 0x30, v142
	v_ashrrev_i32_e32 v247, 31, v246
	v_lshlrev_b64 v[246:247], 11, v[246:247]
	v_lshl_add_u64 v[246:247], v[246:247], 0, v[140:141]
	v_lshlrev_b64 v[246:247], 2, v[246:247]
	v_lshl_add_u64 v[248:249], s[78:79], 0, v[246:247]
	global_load_dwordx4 v[214:217], v[248:249], off nt
	global_load_dwordx4 v[218:221], v[248:249], off offset:64 nt
	global_load_dwordx4 v[222:225], v[248:249], off offset:512 nt
	global_load_dwordx4 v[226:229], v[248:249], off offset:576 nt
	v_or_b32_e32 v246, 0x80, v142
	v_ashrrev_i32_e32 v247, 31, v246
	v_lshlrev_b64 v[246:247], 11, v[246:247]
	v_lshl_add_u64 v[246:247], v[246:247], 0, v[140:141]
	v_lshlrev_b64 v[246:247], 2, v[246:247]
	v_lshl_add_u64 v[248:249], s[78:79], 0, v[246:247]
	global_load_dwordx4 v[230:233], v[248:249], off nt
	global_load_dwordx4 v[234:237], v[248:249], off offset:64 nt
	global_load_dwordx4 v[238:241], v[248:249], off offset:512 nt
	global_load_dwordx4 v[242:245], v[248:249], off offset:576 nt
	s_waitcnt vmcnt(16)
	v_pk_add_f32 v[160:161], v[124:125], v[160:161]
	v_pk_add_f32 v[162:163], v[126:127], v[162:163]
	v_pk_add_f32 v[164:165], v[120:121], v[164:165]
	v_pk_add_f32 v[166:167], v[122:123], v[166:167]
	v_pk_add_f32 v[168:169], v[108:109], v[168:169]
	v_pk_add_f32 v[170:171], v[110:111], v[170:171]
	v_pk_add_f32 v[172:173], v[104:105], v[172:173]
	v_pk_add_f32 v[174:175], v[106:107], v[174:175]
	v_mov_b32_e32 v246, v142
	v_ashrrev_i32_e32 v247, 31, v246
	v_lshlrev_b64 v[246:247], 11, v[246:247]
	v_lshl_add_u64 v[246:247], v[246:247], 0, v[140:141]
	v_lshlrev_b64 v[246:247], 2, v[246:247]
	v_lshl_add_u64 v[250:251], s[78:79], 0, v[246:247]
	global_store_dwordx4 v[250:251], v[160:163], off nt
	global_store_dwordx4 v[250:251], v[164:167], off offset:64 nt
	global_store_dwordx4 v[250:251], v[168:171], off offset:512 nt
	global_store_dwordx4 v[250:251], v[172:175], off offset:576 nt
	v_or_b32_e32 v246, 0x90, v142
	v_ashrrev_i32_e32 v247, 31, v246
	v_lshlrev_b64 v[246:247], 11, v[246:247]
	v_lshl_add_u64 v[246:247], v[246:247], 0, v[140:141]
	v_lshlrev_b64 v[246:247], 2, v[246:247]
	v_lshl_add_u64 v[248:249], s[78:79], 0, v[246:247]
	global_load_dwordx4 v[160:163], v[248:249], off nt
	global_load_dwordx4 v[164:167], v[248:249], off offset:64 nt
	global_load_dwordx4 v[168:171], v[248:249], off offset:512 nt
	global_load_dwordx4 v[172:175], v[248:249], off offset:576 nt
	s_waitcnt vmcnt(20)
	v_pk_add_f32 v[176:177], v[116:117], v[176:177]
	v_pk_add_f32 v[178:179], v[118:119], v[178:179]
	v_pk_add_f32 v[180:181], v[112:113], v[180:181]
	v_pk_add_f32 v[182:183], v[114:115], v[182:183]
	v_pk_add_f32 v[184:185], v[100:101], v[184:185]
	v_pk_add_f32 v[186:187], v[102:103], v[186:187]
	v_pk_add_f32 v[188:189], v[96:97], v[188:189]
	v_pk_add_f32 v[190:191], v[98:99], v[190:191]
	v_or_b32_e32 v246, 0x10, v142
	v_ashrrev_i32_e32 v247, 31, v246
	v_lshlrev_b64 v[246:247], 11, v[246:247]
	v_lshl_add_u64 v[246:247], v[246:247], 0, v[140:141]
	v_lshlrev_b64 v[246:247], 2, v[246:247]
	v_lshl_add_u64 v[250:251], s[78:79], 0, v[246:247]
	global_store_dwordx4 v[250:251], v[176:179], off nt
	global_store_dwordx4 v[250:251], v[180:183], off offset:64 nt
	global_store_dwordx4 v[250:251], v[184:187], off offset:512 nt
	global_store_dwordx4 v[250:251], v[188:191], off offset:576 nt
	v_or_b32_e32 v246, 0xa0, v142
	v_ashrrev_i32_e32 v247, 31, v246
	v_lshlrev_b64 v[246:247], 11, v[246:247]
	v_lshl_add_u64 v[246:247], v[246:247], 0, v[140:141]
	v_lshlrev_b64 v[246:247], 2, v[246:247]
	v_lshl_add_u64 v[248:249], s[78:79], 0, v[246:247]
	global_load_dwordx4 v[176:179], v[248:249], off nt
	global_load_dwordx4 v[180:183], v[248:249], off offset:64 nt
	global_load_dwordx4 v[184:187], v[248:249], off offset:512 nt
	global_load_dwordx4 v[188:191], v[248:249], off offset:576 nt
	s_waitcnt vmcnt(24)
	v_pk_add_f32 v[192:193], v[92:93], v[192:193]
	v_pk_add_f32 v[194:195], v[94:95], v[194:195]
	v_pk_add_f32 v[196:197], v[88:89], v[196:197]
	v_pk_add_f32 v[198:199], v[90:91], v[198:199]
	v_pk_add_f32 v[200:201], v[76:77], v[200:201]
	v_pk_add_f32 v[202:203], v[78:79], v[202:203]
	v_pk_add_f32 v[204:205], v[72:73], v[204:205]
	v_pk_add_f32 v[206:207], v[74:75], v[206:207]
	v_or_b32_e32 v246, 0x20, v142
	v_ashrrev_i32_e32 v247, 31, v246
	v_lshlrev_b64 v[246:247], 11, v[246:247]
	v_lshl_add_u64 v[246:247], v[246:247], 0, v[140:141]
	v_lshlrev_b64 v[246:247], 2, v[246:247]
	v_lshl_add_u64 v[250:251], s[78:79], 0, v[246:247]
	global_store_dwordx4 v[250:251], v[192:195], off nt
	global_store_dwordx4 v[250:251], v[196:199], off offset:64 nt
	global_store_dwordx4 v[250:251], v[200:203], off offset:512 nt
	global_store_dwordx4 v[250:251], v[204:207], off offset:576 nt
	v_or_b32_e32 v246, 0xb0, v142
	v_ashrrev_i32_e32 v247, 31, v246
	v_lshlrev_b64 v[246:247], 11, v[246:247]
	v_lshl_add_u64 v[246:247], v[246:247], 0, v[140:141]
	v_lshlrev_b64 v[246:247], 2, v[246:247]
	v_lshl_add_u64 v[248:249], s[78:79], 0, v[246:247]
	global_load_dwordx4 v[192:195], v[248:249], off nt
	global_load_dwordx4 v[196:199], v[248:249], off offset:64 nt
	global_load_dwordx4 v[200:203], v[248:249], off offset:512 nt
	global_load_dwordx4 v[204:207], v[248:249], off offset:576 nt
	s_waitcnt vmcnt(28)
	v_pk_add_f32 v[214:215], v[84:85], v[214:215]
	v_pk_add_f32 v[216:217], v[86:87], v[216:217]
	v_pk_add_f32 v[218:219], v[80:81], v[218:219]
	v_pk_add_f32 v[220:221], v[82:83], v[220:221]
	v_pk_add_f32 v[222:223], v[68:69], v[222:223]
	v_pk_add_f32 v[224:225], v[70:71], v[224:225]
	v_pk_add_f32 v[226:227], v[64:65], v[226:227]
	v_pk_add_f32 v[228:229], v[66:67], v[228:229]
	v_or_b32_e32 v246, 0x30, v142
	v_ashrrev_i32_e32 v247, 31, v246
	v_lshlrev_b64 v[246:247], 11, v[246:247]
	v_lshl_add_u64 v[246:247], v[246:247], 0, v[140:141]
	v_lshlrev_b64 v[246:247], 2, v[246:247]
	v_lshl_add_u64 v[250:251], s[78:79], 0, v[246:247]
	global_store_dwordx4 v[250:251], v[214:217], off nt
	global_store_dwordx4 v[250:251], v[218:221], off offset:64 nt
	global_store_dwordx4 v[250:251], v[222:225], off offset:512 nt
	global_store_dwordx4 v[250:251], v[226:229], off offset:576 nt
	s_waitcnt vmcnt(28)
	v_pk_add_f32 v[230:231], v[60:61], v[230:231]
	v_pk_add_f32 v[232:233], v[62:63], v[232:233]
	v_pk_add_f32 v[234:235], v[56:57], v[234:235]
	v_pk_add_f32 v[236:237], v[58:59], v[236:237]
	v_pk_add_f32 v[238:239], v[44:45], v[238:239]
	v_pk_add_f32 v[240:241], v[46:47], v[240:241]
	v_pk_add_f32 v[242:243], v[40:41], v[242:243]
	v_pk_add_f32 v[244:245], v[42:43], v[244:245]
	v_or_b32_e32 v246, 0x80, v142
	v_ashrrev_i32_e32 v247, 31, v246
	v_lshlrev_b64 v[246:247], 11, v[246:247]
	v_lshl_add_u64 v[246:247], v[246:247], 0, v[140:141]
	v_lshlrev_b64 v[246:247], 2, v[246:247]
	v_lshl_add_u64 v[250:251], s[78:79], 0, v[246:247]
	global_store_dwordx4 v[250:251], v[230:233], off nt
	global_store_dwordx4 v[250:251], v[234:237], off offset:64 nt
	global_store_dwordx4 v[250:251], v[238:241], off offset:512 nt
	global_store_dwordx4 v[250:251], v[242:245], off offset:576 nt
	s_waitcnt vmcnt(24)
	v_pk_add_f32 v[160:161], v[52:53], v[160:161]
	v_pk_add_f32 v[162:163], v[54:55], v[162:163]
	v_pk_add_f32 v[164:165], v[48:49], v[164:165]
	v_pk_add_f32 v[166:167], v[50:51], v[166:167]
	v_pk_add_f32 v[168:169], v[36:37], v[168:169]
	v_pk_add_f32 v[170:171], v[38:39], v[170:171]
	v_pk_add_f32 v[172:173], v[32:33], v[172:173]
	v_pk_add_f32 v[174:175], v[34:35], v[174:175]
	v_or_b32_e32 v246, 0x90, v142
	v_ashrrev_i32_e32 v247, 31, v246
	v_lshlrev_b64 v[246:247], 11, v[246:247]
	v_lshl_add_u64 v[246:247], v[246:247], 0, v[140:141]
	v_lshlrev_b64 v[246:247], 2, v[246:247]
	v_lshl_add_u64 v[250:251], s[78:79], 0, v[246:247]
	global_store_dwordx4 v[250:251], v[160:163], off nt
	global_store_dwordx4 v[250:251], v[164:167], off offset:64 nt
	global_store_dwordx4 v[250:251], v[168:171], off offset:512 nt
	global_store_dwordx4 v[250:251], v[172:175], off offset:576 nt
	s_waitcnt vmcnt(20)
	v_pk_add_f32 v[176:177], v[28:29], v[176:177]
	v_pk_add_f32 v[178:179], v[30:31], v[178:179]
	v_pk_add_f32 v[180:181], v[24:25], v[180:181]
	v_pk_add_f32 v[182:183], v[26:27], v[182:183]
	v_pk_add_f32 v[184:185], v[12:13], v[184:185]
	v_pk_add_f32 v[186:187], v[14:15], v[186:187]
	v_pk_add_f32 v[188:189], v[8:9], v[188:189]
	v_pk_add_f32 v[190:191], v[10:11], v[190:191]
	v_or_b32_e32 v246, 0xa0, v142
	v_ashrrev_i32_e32 v247, 31, v246
	v_lshlrev_b64 v[246:247], 11, v[246:247]
	v_lshl_add_u64 v[246:247], v[246:247], 0, v[140:141]
	v_lshlrev_b64 v[246:247], 2, v[246:247]
	v_lshl_add_u64 v[250:251], s[78:79], 0, v[246:247]
	global_store_dwordx4 v[250:251], v[176:179], off nt
	global_store_dwordx4 v[250:251], v[180:183], off offset:64 nt
	global_store_dwordx4 v[250:251], v[184:187], off offset:512 nt
	global_store_dwordx4 v[250:251], v[188:191], off offset:576 nt
	s_waitcnt vmcnt(16)
	v_pk_add_f32 v[192:193], v[20:21], v[192:193]
	v_pk_add_f32 v[194:195], v[22:23], v[194:195]
	v_pk_add_f32 v[196:197], v[16:17], v[196:197]
	v_pk_add_f32 v[198:199], v[18:19], v[198:199]
	v_pk_add_f32 v[200:201], v[4:5], v[200:201]
	v_pk_add_f32 v[202:203], v[6:7], v[202:203]
	v_pk_add_f32 v[204:205], v[0:1], v[204:205]
	v_pk_add_f32 v[206:207], v[2:3], v[206:207]
	v_or_b32_e32 v246, 0xb0, v142
	v_ashrrev_i32_e32 v247, 31, v246
	v_lshlrev_b64 v[246:247], 11, v[246:247]
	v_lshl_add_u64 v[246:247], v[246:247], 0, v[140:141]
	v_lshlrev_b64 v[246:247], 2, v[246:247]
	v_lshl_add_u64 v[250:251], s[78:79], 0, v[246:247]
	global_store_dwordx4 v[250:251], v[192:195], off nt
	global_store_dwordx4 v[250:251], v[196:199], off offset:64 nt
	global_store_dwordx4 v[250:251], v[200:203], off offset:512 nt
	global_store_dwordx4 v[250:251], v[204:207], off offset:576 nt
	s_cbranch_vccnz .LBB0_1336
	s_andn2_b64 vcc, exec, s[0:1]
	s_cbranch_vccnz .LBB0_1335
	s_barrier
	s_branch .LBB0_1335
